# GEMM1 K-loop first load segment: all 16 ds_reads issued before the scalar address math (both layers), on top of the fourth combination
# speedup vs baseline: 1.0045x; 1.0022x over previous
; #define PG8_STAGE(bufoff, gbase, voff) do { _Pragma("unroll") for (int _i = 0; _i < 2; ++_i) \
;         __builtin_amdgcn_global_load_lds((const unsigned*)((const char*)(gbase) + (voff)[_i]), (PG8_LAS unsigned*)(lds + (bufoff) + ldsw + _i * 8192), 16, 0, 0); } while (0)
; #define PG8_LDA(dst, b, h) do { _Pragma("unroll") for (int m = 0; m < 4; ++m) _Pragma("unroll") for (int k = 0; k < 2; ++k) dst[m][k] = *(const PG8_LAS bf16x8*)(lds + PG8_SA(b, h) + aoff + m * 2048 + k * 1024); } while (0)
; #define PG8_LDB(dst, b, h) do { _Pragma("unroll") for (int n = 0; n < 2; ++n) _Pragma("unroll") for (int k = 0; k < 2; ++k) dst[n][k] = *(const PG8_LAS bf16x8*)(lds + PG8_SB(b, h) + boff + n * 2048 + k * 1024); } while (0)
; #define PG8_MMA(ai, bj, At, Bt) do { __builtin_amdgcn_s_setprio(1); _Pragma("unroll") for (int m = 0; m < 4; ++m) _Pragma("unroll") for (int n = 0; n < 2; ++n) _Pragma("unroll") for (int k = 0; k < 2; ++k) \
;         acc[ai][bj][m][n] = Gemm::i8 ? ::mfma16i8_g(Bt[n][k], At[m][k], acc[ai][bj][m][n]) : ::mfma16_g(Bt[n][k], At[m][k], acc[ai][bj][m][n]); __builtin_amdgcn_s_setprio(0); } while (0)
; #define PG8_WAIT_V(n) asm volatile("s_waitcnt vmcnt(" #n ")" ::: "memory")
; #define PG8_WAIT_L(n) asm volatile("s_waitcnt lgkmcnt(" #n ")" ::: "memory")
; template <class Epi, class Sched, class Gemm, bool ALIGN_EPI = false, bool SP2 = false>
; __device__ __forceinline__ void gemm_phase(PG8_LAS unsigned char* lds, const Gemm g, const Sched& S, const Epi& E) {
;     ...
;             PG8_LDB(B0, 0, 0); PG8_LDB(B1, 0, 1); PG8_SCHED; PG8_LDA(At, 0, 0); PG8_STAGE(PG8_SA(1, 1), a1 + hstepA, voffA);
;             PG8_WAIT_V(8); PG8_WAIT_L(0); PG8_BAR; PG8_MMA(0, 0, At, B0); PG8_MMA(0, 1, At, B1); PG8_BAR; PG8_SCHED;
;             PG8_LDA(At, 0, 1); PG8_STAGE(PG8_SB(0, 0), b2, voffB); PG8_STAGE(PG8_SB(0, 1), b2 + hB1, voffB1); PG8_STAGE(PG8_SA(0, 0), a2, voffA);
;             PG8_WAIT_V(8); PG8_WAIT_L(0); PG8_BAR; PG8_MMA(1, 0, At, B0); PG8_MMA(1, 1, At, B1); PG8_BAR; PG8_SCHED;
;             PG8_LDB(B0, 1, 0); PG8_LDB(B1, 1, 1); PG8_SCHED; PG8_LDA(At, 1, 0); PG8_STAGE(PG8_SA(0, 1), a2 + hstepA, voffA);
;             PG8_WAIT_V(8); PG8_WAIT_L(0); PG8_BAR; PG8_MMA(0, 0, At, B0); PG8_MMA(0, 1, At, B1); PG8_BAR; PG8_SCHED;
;             PG8_LDA(At, 1, 1); PG8_STAGE(PG8_SB(1, 0), b3, voffB); PG8_STAGE(PG8_SB(1, 1), b3 + hB1, voffB1); PG8_STAGE(PG8_SA(1, 0), a3, voffA);
.LBB0_136:
	ds_read_b128 v[174:177], v253
	ds_read_b128 v[170:173], v253 offset:1024
	ds_read_b128 v[166:169], v253 offset:2048
	ds_read_b128 v[162:165], v253 offset:3072
	ds_read_b128 v[158:161], v254
	ds_read_b128 v[154:157], v254 offset:1024
	ds_read_b128 v[150:153], v254 offset:2048
	ds_read_b128 v[146:149], v254 offset:3072
	ds_read_b128 v[190:193], v222
	ds_read_b128 v[194:197], v222 offset:1024
	ds_read_b128 v[198:201], v222 offset:2048
	ds_read_b128 v[202:205], v222 offset:3072
	ds_read_b128 v[206:209], v222 offset:4096
	ds_read_b128 v[186:189], v222 offset:5120
	ds_read_b128 v[182:185], v222 offset:6144
	ds_read_b128 v[178:181], v222 offset:7168
	s_add_u32 s0, s48, 0xfffe0080
	s_addc_u32 s1, s49, -1
	s_cmp_eq_u32 s2, 4
	s_cselect_b32 s53, s7, s1
	s_cselect_b32 s52, s43, s0
	s_cselect_b32 s55, s79, s82
	s_cselect_b32 s54, s80, s81
	s_add_i32 s95, s76, s64
	s_add_i32 m0, s65, 0xc000
	s_add_i32 s96, s65, 0xe000
	s_add_i32 s92, s95, 0x2000
	s_add_u32 s56, s54, 0x20000
	s_addc_u32 s57, s55, 0
	s_add_i32 s94, s77, s64
	s_add_i32 s93, s94, 0x2000
	s_add_i32 s91, 0, 0x18000
	s_add_i32 s90, 0, 0x1c000
	s_add_u32 s50, s52, 0x20000
	s_addc_u32 s51, s53, 0
	s_add_i32 s83, s91, s64
	s_add_i32 s3, s83, 0x2000
	s_add_u32 s0, s54, 0x20080
	s_addc_u32 s1, s55, 0
	s_add_i32 s89, s90, s64
	s_add_i32 s88, s89, 0x2000
	s_cmp_lg_u32 s2, 4
	global_load_lds_dwordx4 v220, s[48:49]
	s_mov_b32 m0, s96
	s_nop 0
	global_load_lds_dwordx4 v218, s[48:49]
	s_waitcnt vmcnt(8)
	s_waitcnt lgkmcnt(0)
	s_nop 0
	s_barrier
	s_setprio 1
	v_mfma_i32_16x16x64_i8 v[142:145], v[174:177], v[190:193], v[142:145]
	v_mfma_i32_16x16x64_i8 v[138:141], v[166:169], v[190:193], v[138:141]
	v_mfma_i32_16x16x64_i8 v[126:129], v[174:177], v[198:201], v[126:129]
	v_mfma_i32_16x16x64_i8 v[122:125], v[166:169], v[198:201], v[122:125]
	v_mfma_i32_16x16x64_i8 v[110:113], v[174:177], v[206:209], v[110:113]
	v_mfma_i32_16x16x64_i8 v[106:109], v[166:169], v[206:209], v[106:109]
	v_mfma_i32_16x16x64_i8 v[94:97], v[174:177], v[182:185], v[94:97]
	v_mfma_i32_16x16x64_i8 v[90:93], v[166:169], v[182:185], v[90:93]
	v_mfma_i32_16x16x64_i8 v[142:145], v[170:173], v[194:197], v[142:145]
	v_mfma_i32_16x16x64_i8 v[138:141], v[162:165], v[194:197], v[138:141]
	v_mfma_i32_16x16x64_i8 v[126:129], v[170:173], v[202:205], v[126:129]
	v_mfma_i32_16x16x64_i8 v[122:125], v[162:165], v[202:205], v[122:125]
	v_mfma_i32_16x16x64_i8 v[110:113], v[170:173], v[186:189], v[110:113]
	v_mfma_i32_16x16x64_i8 v[106:109], v[162:165], v[186:189], v[106:109]
	v_mfma_i32_16x16x64_i8 v[94:97], v[170:173], v[178:181], v[94:97]
	v_mfma_i32_16x16x64_i8 v[90:93], v[162:165], v[178:181], v[90:93]
	s_setprio 0
	s_setprio 1
	v_mfma_i32_16x16x64_i8 v[134:137], v[158:161], v[190:193], v[134:137]
	v_mfma_i32_16x16x64_i8 v[130:133], v[150:153], v[190:193], v[130:133]
	v_mfma_i32_16x16x64_i8 v[118:121], v[158:161], v[198:201], v[118:121]
	v_mfma_i32_16x16x64_i8 v[114:117], v[150:153], v[198:201], v[114:117]
	v_mfma_i32_16x16x64_i8 v[102:105], v[158:161], v[206:209], v[102:105]
	v_mfma_i32_16x16x64_i8 v[98:101], v[150:153], v[206:209], v[98:101]
	v_mfma_i32_16x16x64_i8 v[86:89], v[158:161], v[182:185], v[86:89]
	v_mfma_i32_16x16x64_i8 v[82:85], v[150:153], v[182:185], v[82:85]
	v_mfma_i32_16x16x64_i8 v[134:137], v[154:157], v[194:197], v[134:137]
	v_mfma_i32_16x16x64_i8 v[130:133], v[146:149], v[194:197], v[130:133]
	v_mfma_i32_16x16x64_i8 v[118:121], v[154:157], v[202:205], v[118:121]
	v_mfma_i32_16x16x64_i8 v[114:117], v[146:149], v[202:205], v[114:117]
	v_mfma_i32_16x16x64_i8 v[102:105], v[154:157], v[186:189], v[102:105]
	v_mfma_i32_16x16x64_i8 v[98:101], v[146:149], v[186:189], v[98:101]
	v_mfma_i32_16x16x64_i8 v[86:89], v[154:157], v[178:181], v[86:89]
	v_mfma_i32_16x16x64_i8 v[82:85], v[146:149], v[178:181], v[82:85]
	s_setprio 0
	s_barrier
	s_mov_b32 m0, s95
	v_lshl_add_u64 v[242:243], s[54:55], 0, v[212:213]
	ds_read_b128 v[190:193], v222 offset:16384
	ds_read_b128 v[194:197], v222 offset:17408
	ds_read_b128 v[198:201], v222 offset:18432
	ds_read_b128 v[202:205], v222 offset:19456
	ds_read_b128 v[206:209], v222 offset:20480
	ds_read_b128 v[186:189], v222 offset:21504
	ds_read_b128 v[182:185], v222 offset:22528
	ds_read_b128 v[178:181], v222 offset:23552
	global_load_lds_dwordx4 v212, s[54:55]
	v_lshl_add_u64 v[244:245], s[54:55], 0, v[216:217]
	s_mov_b32 m0, s92
	v_lshl_add_u64 v[246:247], s[56:57], 0, v[212:213]
	global_load_lds_dwordx4 v216, s[54:55]
	s_mov_b32 m0, s94
	v_lshl_add_u64 v[248:249], s[52:53], 0, v[214:215]
	global_load_lds_dwordx4 v212, s[56:57]
	s_mov_b32 m0, s93
	s_nop 0
	global_load_lds_dwordx4 v216, s[56:57]
	v_lshl_add_u64 v[246:247], s[52:53], 0, v[210:211]
	s_mov_b32 m0, s65
	s_nop 0
	global_load_lds_dwordx4 v210, s[52:53]
	s_mov_b32 m0, s66
	s_nop 0
	global_load_lds_dwordx4 v214, s[52:53]
	s_waitcnt vmcnt(8)
	s_waitcnt lgkmcnt(0)
	s_nop 0
	s_barrier
; #define PG8_STAGE(bufoff, gbase, voff) do { _Pragma("unroll") for (int _i = 0; _i < 2; ++_i) \
;         __builtin_amdgcn_global_load_lds((const unsigned*)((const char*)(gbase) + (voff)[_i]), (PG8_LAS unsigned*)(lds + (bufoff) + ldsw + _i * 8192), 16, 0, 0); } while (0)
; #define PG8_LDA(dst, b, h) do { _Pragma("unroll") for (int m = 0; m < 4; ++m) _Pragma("unroll") for (int k = 0; k < 2; ++k) dst[m][k] = *(const PG8_LAS bf16x8*)(lds + PG8_SA(b, h) + aoff + m * 2048 + k * 1024); } while (0)
; #define PG8_LDB(dst, b, h) do { _Pragma("unroll") for (int n = 0; n < 2; ++n) _Pragma("unroll") for (int k = 0; k < 2; ++k) dst[n][k] = *(const PG8_LAS bf16x8*)(lds + PG8_SB(b, h) + boff + n * 2048 + k * 1024); } while (0)
; #define PG8_MMA(ai, bj, At, Bt) do { __builtin_amdgcn_s_setprio(1); _Pragma("unroll") for (int m = 0; m < 4; ++m) _Pragma("unroll") for (int n = 0; n < 2; ++n) _Pragma("unroll") for (int k = 0; k < 2; ++k) \
;         acc[ai][bj][m][n] = Gemm::i8 ? ::mfma16i8_g(Bt[n][k], At[m][k], acc[ai][bj][m][n]) : ::mfma16_g(Bt[n][k], At[m][k], acc[ai][bj][m][n]); __builtin_amdgcn_s_setprio(0); } while (0)
; #define PG8_WAIT_V(n) asm volatile("s_waitcnt vmcnt(" #n ")" ::: "memory")
; #define PG8_WAIT_L(n) asm volatile("s_waitcnt lgkmcnt(" #n ")" ::: "memory")
; template <class Epi, class Sched, class Gemm, bool ALIGN_EPI = false, bool SP2 = false>
; __device__ __forceinline__ void gemm_phase(PG8_LAS unsigned char* lds, const Gemm g, const Sched& S, const Epi& E) {
;     ...
;             PG8_LDB(B0, 0, 0); PG8_LDB(B1, 0, 1); PG8_SCHED; PG8_LDA(At, 0, 0); PG8_STAGE(PG8_SA(1, 1), a1 + hstepA, voffA);
;             PG8_WAIT_V(8); PG8_WAIT_L(0); PG8_BAR; PG8_MMA(0, 0, At, B0); PG8_MMA(0, 1, At, B1); PG8_BAR; PG8_SCHED;
;             PG8_LDA(At, 0, 1); PG8_STAGE(PG8_SB(0, 0), b2, voffB); PG8_STAGE(PG8_SB(0, 1), b2 + hB1, voffB1); PG8_STAGE(PG8_SA(0, 0), a2, voffA);
;             PG8_WAIT_V(8); PG8_WAIT_L(0); PG8_BAR; PG8_MMA(1, 0, At, B0); PG8_MMA(1, 1, At, B1); PG8_BAR; PG8_SCHED;
;             PG8_LDB(B0, 1, 0); PG8_LDB(B1, 1, 1); PG8_SCHED; PG8_LDA(At, 1, 0); PG8_STAGE(PG8_SA(0, 1), a2 + hstepA, voffA);
;             PG8_WAIT_V(8); PG8_WAIT_L(0); PG8_BAR; PG8_MMA(0, 0, At, B0); PG8_MMA(0, 1, At, B1); PG8_BAR; PG8_SCHED;
;             PG8_LDA(At, 1, 1); PG8_STAGE(PG8_SB(1, 0), b3, voffB); PG8_STAGE(PG8_SB(1, 1), b3 + hB1, voffB1); PG8_STAGE(PG8_SA(1, 0), a3, voffA);
	s_setprio 1
	v_mfma_i32_16x16x64_i8 v[78:81], v[174:177], v[190:193], v[78:81]
	v_mfma_i32_16x16x64_i8 v[74:77], v[166:169], v[190:193], v[74:77]
	v_mfma_i32_16x16x64_i8 v[62:65], v[174:177], v[198:201], v[62:65]
	v_mfma_i32_16x16x64_i8 v[58:61], v[166:169], v[198:201], v[58:61]
	v_mfma_i32_16x16x64_i8 v[46:49], v[174:177], v[206:209], v[46:49]
	v_mfma_i32_16x16x64_i8 v[42:45], v[166:169], v[206:209], v[42:45]
	v_mfma_i32_16x16x64_i8 v[30:33], v[174:177], v[182:185], v[30:33]
	v_mfma_i32_16x16x64_i8 v[26:29], v[166:169], v[182:185], v[26:29]
	v_mfma_i32_16x16x64_i8 v[78:81], v[170:173], v[194:197], v[78:81]
	v_mfma_i32_16x16x64_i8 v[74:77], v[162:165], v[194:197], v[74:77]
	v_mfma_i32_16x16x64_i8 v[62:65], v[170:173], v[202:205], v[62:65]
	v_mfma_i32_16x16x64_i8 v[58:61], v[162:165], v[202:205], v[58:61]
	v_mfma_i32_16x16x64_i8 v[46:49], v[170:173], v[186:189], v[46:49]
	v_mfma_i32_16x16x64_i8 v[42:45], v[162:165], v[186:189], v[42:45]
	v_mfma_i32_16x16x64_i8 v[30:33], v[170:173], v[178:181], v[30:33]
	v_mfma_i32_16x16x64_i8 v[26:29], v[162:165], v[178:181], v[26:29]
	s_setprio 0
	s_setprio 1
	v_mfma_i32_16x16x64_i8 v[70:73], v[158:161], v[190:193], v[70:73]
	v_mfma_i32_16x16x64_i8 v[66:69], v[150:153], v[190:193], v[66:69]
	v_mfma_i32_16x16x64_i8 v[54:57], v[158:161], v[198:201], v[54:57]
	v_mfma_i32_16x16x64_i8 v[50:53], v[150:153], v[198:201], v[50:53]
	v_mfma_i32_16x16x64_i8 v[38:41], v[158:161], v[206:209], v[38:41]
	v_mfma_i32_16x16x64_i8 v[34:37], v[150:153], v[206:209], v[34:37]
	v_mfma_i32_16x16x64_i8 v[22:25], v[158:161], v[182:185], v[22:25]
	v_mfma_i32_16x16x64_i8 v[18:21], v[150:153], v[182:185], v[18:21]
	v_mfma_i32_16x16x64_i8 v[70:73], v[154:157], v[194:197], v[70:73]
	v_mfma_i32_16x16x64_i8 v[66:69], v[146:149], v[194:197], v[66:69]
	v_mfma_i32_16x16x64_i8 v[54:57], v[154:157], v[202:205], v[54:57]
	v_mfma_i32_16x16x64_i8 v[50:53], v[146:149], v[202:205], v[50:53]
	v_mfma_i32_16x16x64_i8 v[38:41], v[154:157], v[186:189], v[38:41]
	v_mfma_i32_16x16x64_i8 v[34:37], v[146:149], v[186:189], v[34:37]
	v_mfma_i32_16x16x64_i8 v[22:25], v[154:157], v[178:181], v[22:25]
	v_mfma_i32_16x16x64_i8 v[18:21], v[146:149], v[178:181], v[18:21]
	s_setprio 0
	s_barrier
	v_add_u32_e32 v146, s91, v251
	ds_read_b128 v[174:177], v146
	ds_read_b128 v[170:173], v146 offset:1024
	ds_read_b128 v[166:169], v146 offset:2048
	ds_read_b128 v[162:165], v146 offset:3072
	v_add_u32_e32 v146, s90, v251
	ds_read_b128 v[150:153], v146
	ds_read_b128 v[154:157], v146 offset:1024
	ds_read_b128 v[158:161], v146 offset:2048
	ds_read_b128 v[146:149], v146 offset:3072
	s_mov_b32 m0, s67
	ds_read_b128 v[190:193], v222 offset:32768
	ds_read_b128 v[194:197], v222 offset:33792
	ds_read_b128 v[198:201], v222 offset:34816
	ds_read_b128 v[202:205], v222 offset:35840
	ds_read_b128 v[206:209], v222 offset:36864
	ds_read_b128 v[186:189], v222 offset:37888
	ds_read_b128 v[182:185], v222 offset:38912
	ds_read_b128 v[178:181], v222 offset:39936
	global_load_lds_dwordx4 v210, s[50:51]
	s_mov_b32 m0, s68
	s_nop 0
	global_load_lds_dwordx4 v214, s[50:51]
	s_waitcnt vmcnt(8)
	s_waitcnt lgkmcnt(0)
	s_nop 0
	s_barrier
	s_setprio 1
	v_mfma_i32_16x16x64_i8 v[142:145], v[174:177], v[190:193], v[142:145]
	v_mfma_i32_16x16x64_i8 v[138:141], v[166:169], v[190:193], v[138:141]
	v_mfma_i32_16x16x64_i8 v[126:129], v[174:177], v[198:201], v[126:129]
	v_mfma_i32_16x16x64_i8 v[122:125], v[166:169], v[198:201], v[122:125]
	v_mfma_i32_16x16x64_i8 v[110:113], v[174:177], v[206:209], v[110:113]
	v_mfma_i32_16x16x64_i8 v[106:109], v[166:169], v[206:209], v[106:109]
	v_mfma_i32_16x16x64_i8 v[94:97], v[174:177], v[182:185], v[94:97]
	v_mfma_i32_16x16x64_i8 v[90:93], v[166:169], v[182:185], v[90:93]
	v_mfma_i32_16x16x64_i8 v[142:145], v[170:173], v[194:197], v[142:145]
	v_mfma_i32_16x16x64_i8 v[138:141], v[162:165], v[194:197], v[138:141]
	v_mfma_i32_16x16x64_i8 v[126:129], v[170:173], v[202:205], v[126:129]
	v_mfma_i32_16x16x64_i8 v[122:125], v[162:165], v[202:205], v[122:125]
	v_mfma_i32_16x16x64_i8 v[110:113], v[170:173], v[186:189], v[110:113]
	v_mfma_i32_16x16x64_i8 v[106:109], v[162:165], v[186:189], v[106:109]
	v_mfma_i32_16x16x64_i8 v[94:97], v[170:173], v[178:181], v[94:97]
	v_mfma_i32_16x16x64_i8 v[90:93], v[162:165], v[178:181], v[90:93]
	s_setprio 0
	s_setprio 1
	v_mfma_i32_16x16x64_i8 v[134:137], v[150:153], v[190:193], v[134:137]
	v_mfma_i32_16x16x64_i8 v[130:133], v[158:161], v[190:193], v[130:133]
	v_mfma_i32_16x16x64_i8 v[118:121], v[150:153], v[198:201], v[118:121]
	v_mfma_i32_16x16x64_i8 v[114:117], v[158:161], v[198:201], v[114:117]
	v_mfma_i32_16x16x64_i8 v[102:105], v[150:153], v[206:209], v[102:105]
	v_mfma_i32_16x16x64_i8 v[98:101], v[158:161], v[206:209], v[98:101]
	v_mfma_i32_16x16x64_i8 v[86:89], v[150:153], v[182:185], v[86:89]
	v_mfma_i32_16x16x64_i8 v[82:85], v[158:161], v[182:185], v[82:85]
	v_mfma_i32_16x16x64_i8 v[134:137], v[154:157], v[194:197], v[134:137]
	v_mfma_i32_16x16x64_i8 v[130:133], v[146:149], v[194:197], v[130:133]
	v_mfma_i32_16x16x64_i8 v[118:121], v[154:157], v[202:205], v[118:121]
	v_mfma_i32_16x16x64_i8 v[114:117], v[146:149], v[202:205], v[114:117]
	v_mfma_i32_16x16x64_i8 v[102:105], v[154:157], v[186:189], v[102:105]
	v_mfma_i32_16x16x64_i8 v[98:101], v[146:149], v[186:189], v[98:101]
	v_mfma_i32_16x16x64_i8 v[86:89], v[154:157], v[178:181], v[86:89]
	v_mfma_i32_16x16x64_i8 v[82:85], v[146:149], v[178:181], v[82:85]
	s_setprio 0
	s_barrier
	s_mov_b32 m0, s83
	v_lshl_add_u64 v[224:225], v[242:243], 0, s[36:37]
	ds_read_b128 v[206:209], v222 offset:49152
	ds_read_b128 v[202:205], v222 offset:50176
	ds_read_b128 v[194:197], v222 offset:51200
	ds_read_b128 v[198:201], v222 offset:52224
	ds_read_b128 v[186:189], v222 offset:53248
	ds_read_b128 v[190:193], v222 offset:54272
	ds_read_b128 v[182:185], v222 offset:55296
	ds_read_b128 v[178:181], v222 offset:56320
	global_load_lds_dwordx4 v[224:225], off
	v_lshl_add_u64 v[224:225], v[244:245], 0, s[36:37]
	s_mov_b32 m0, s3
	s_nop 0
	global_load_lds_dwordx4 v[224:225], off
	s_mov_b32 m0, s89
	s_nop 0
	global_load_lds_dwordx4 v212, s[0:1]
	s_mov_b32 m0, s88
	s_nop 0
	global_load_lds_dwordx4 v216, s[0:1]
	v_lshl_add_u64 v[224:225], v[246:247], 0, s[36:37]
	s_mov_b32 m0, s72
	s_nop 0
	global_load_lds_dwordx4 v[224:225], off
	v_lshl_add_u64 v[224:225], v[248:249], 0, s[36:37]
	s_mov_b32 m0, s73
	s_nop 0
	global_load_lds_dwordx4 v[224:225], off
	s_waitcnt vmcnt(8)
	s_cbranch_scc1 .LBB0_135
	s_branch .LBB0_135
